# v046 + attention epilogue: O stores paired with v_permlane32_swap into dwordx4 (8 instead of 16 stores per 32 rows)
# speedup vs baseline: 1.0273x; 1.0114x over previous
; __device__ __forceinline__ unsigned pk2(float lo, float hi) { return pg8::cvt_pk_bf16(lo, hi); }
; __device__ __forceinline__ void attn_phase(LAS unsigned char* lds, const bf16* Q, const bf16* Kb, const bf16* VT, const bf16* Kc, const bf16* VcT, bf16* O, const float* relb, int gw, int ngw, int tid) {
;     ...
;         for (int qb = 0; qb < 2; ++qb) { const float lt = lrun[qb] + __shfl_xor(lrun[qb], 32), inv = 1.0f / lt;
;             bf16* orow = O + (size_t)(qrow0 + 32 * qb + q) * 1024 + h * 64;
; #pragma unroll
;             for (int db = 0; db < 2; ++db)
; #pragma unroll
;                 for (int g = 0; g < 4; ++g) { u32x2 w; w.x = pk2(o[qb][db][4 * g] * inv, o[qb][db][4 * g + 1] * inv); w.y = pk2(o[qb][db][4 * g + 2] * inv, o[qb][db][4 * g + 3] * inv);
;                     *(u32x2*)(orow + 32 * db + 8 * g + 4 * hi) = w; } }
.LBB0_262:
	ds_bpermute_b32 v1, v183, v187
	v_add_u32_e32 v66, s16, v182
	s_lshl_b32 s72, s19, 7
	v_lshl_add_u64 v[68:69], v[178:179], 0, s[72:73]
	s_add_i32 s15, s15, 1
	s_waitcnt lgkmcnt(0)
	v_add_f32_e32 v1, v187, v1
	v_div_scale_f32 v67, s[2:3], v1, v1, 1.0
	v_rcp_f32_e32 v70, v67
	s_cmp_eq_u32 s15, s12
	v_fma_f32 v71, -v67, v70, 1.0
	v_fmac_f32_e32 v70, v71, v70
	v_div_scale_f32 v71, vcc, 1.0, v1, 1.0
	v_mul_f32_e32 v72, v71, v70
	v_fma_f32 v73, -v67, v72, v71
	v_fmac_f32_e32 v72, v73, v70
	v_fma_f32 v67, -v67, v72, v71
	v_div_fmas_f32 v67, v67, v70, v72
	v_div_fixup_f32 v1, v67, v1, 1.0
	v_ashrrev_i32_e32 v67, 31, v66
	v_lshlrev_b64 v[70:71], 11, v[66:67]
	v_lshl_add_u64 v[70:71], v[68:69], 0, v[70:71]
	v_bfe_u32 v72, v233, 5, 1
	v_lshlrev_b32_e32 v72, 3, v72
	v_mov_b32_e32 v73, 0
	v_lshl_add_u64 v[70:71], v[70:71], 0, v[72:73]
	v_mul_f32_e32 v50, v50, v1
	v_mul_f32_e32 v51, v51, v1
	v_mul_f32_e32 v52, v52, v1
	v_mul_f32_e32 v53, v53, v1
	v_mul_f32_e32 v54, v54, v1
	v_mul_f32_e32 v55, v55, v1
	v_mul_f32_e32 v56, v56, v1
	v_mul_f32_e32 v57, v57, v1
	v_cvt_pk_bf16_f32 v50, v50, v51
	v_cvt_pk_bf16_f32 v51, v52, v53
	v_cvt_pk_bf16_f32 v52, v54, v55
	v_cvt_pk_bf16_f32 v53, v56, v57
	s_nop 1
	v_permlane32_swap_b32_e32 v50, v52
	v_permlane32_swap_b32_e32 v51, v53
	s_nop 0
	global_store_dwordx4 v[70:71], v[50:53], off
	v_mul_f32_e32 v58, v58, v1
	v_mul_f32_e32 v59, v59, v1
	v_mul_f32_e32 v60, v60, v1
	v_mul_f32_e32 v61, v61, v1
	v_mul_f32_e32 v62, v62, v1
	v_mul_f32_e32 v63, v63, v1
	v_mul_f32_e32 v64, v64, v1
	v_mul_f32_e32 v65, v65, v1
	v_cvt_pk_bf16_f32 v58, v58, v59
	v_cvt_pk_bf16_f32 v59, v60, v61
	v_cvt_pk_bf16_f32 v60, v62, v63
	v_cvt_pk_bf16_f32 v61, v64, v65
	s_nop 1
	v_permlane32_swap_b32_e32 v58, v60
	v_permlane32_swap_b32_e32 v59, v61
	s_nop 0
	global_store_dwordx4 v[70:71], v[58:61], off offset:32
	v_mul_f32_e32 v34, v34, v1
	v_mul_f32_e32 v35, v35, v1
	v_mul_f32_e32 v36, v36, v1
	v_mul_f32_e32 v37, v37, v1
	v_mul_f32_e32 v38, v38, v1
	v_mul_f32_e32 v39, v39, v1
	v_mul_f32_e32 v40, v40, v1
	v_mul_f32_e32 v41, v41, v1
	v_cvt_pk_bf16_f32 v34, v34, v35
	v_cvt_pk_bf16_f32 v35, v36, v37
	v_cvt_pk_bf16_f32 v36, v38, v39
	v_cvt_pk_bf16_f32 v37, v40, v41
	s_nop 1
	v_permlane32_swap_b32_e32 v34, v36
	v_permlane32_swap_b32_e32 v35, v37
	s_nop 0
	global_store_dwordx4 v[70:71], v[34:37], off offset:64
	v_mul_f32_e32 v42, v42, v1
	v_mul_f32_e32 v43, v43, v1
	v_mul_f32_e32 v44, v44, v1
	v_mul_f32_e32 v45, v45, v1
	v_mul_f32_e32 v46, v46, v1
	v_mul_f32_e32 v47, v47, v1
	v_mul_f32_e32 v48, v48, v1
	v_mul_f32_e32 v49, v49, v1
	v_cvt_pk_bf16_f32 v42, v42, v43
	v_cvt_pk_bf16_f32 v43, v44, v45
	v_cvt_pk_bf16_f32 v44, v46, v47
	v_cvt_pk_bf16_f32 v45, v48, v49
	s_nop 1
	v_permlane32_swap_b32_e32 v42, v44
	v_permlane32_swap_b32_e32 v43, v45
	s_nop 0
	global_store_dwordx4 v[70:71], v[42:45], off offset:96
	ds_bpermute_b32 v1, v183, v186
	s_waitcnt lgkmcnt(0)
	v_add_f32_e32 v1, v186, v1
	v_div_scale_f32 v34, s[2:3], v1, v1, 1.0
	v_rcp_f32_e32 v35, v34
	s_nop 0
	v_fma_f32 v36, -v34, v35, 1.0
	v_fmac_f32_e32 v35, v36, v35
	v_div_scale_f32 v36, vcc, 1.0, v1, 1.0
	v_mul_f32_e32 v37, v36, v35
	v_fma_f32 v38, -v34, v37, v36
	v_fmac_f32_e32 v37, v38, v35
	v_fma_f32 v34, -v34, v37, v36
	v_div_fmas_f32 v34, v34, v35, v37
	v_div_fixup_f32 v1, v34, v1, 1.0
	v_add_u32_e32 v34, 32, v66
	v_ashrrev_i32_e32 v35, 31, v34
	v_lshlrev_b64 v[34:35], 11, v[34:35]
	v_lshl_add_u64 v[34:35], v[68:69], 0, v[34:35]
	v_lshl_add_u64 v[34:35], v[34:35], 0, v[72:73]
	v_mul_f32_e32 v18, v18, v1
	v_mul_f32_e32 v19, v19, v1
	v_mul_f32_e32 v20, v20, v1
	v_mul_f32_e32 v21, v21, v1
	v_mul_f32_e32 v22, v22, v1
	v_mul_f32_e32 v23, v23, v1
	v_mul_f32_e32 v24, v24, v1
	v_mul_f32_e32 v25, v25, v1
	v_cvt_pk_bf16_f32 v18, v18, v19
	v_cvt_pk_bf16_f32 v19, v20, v21
	v_cvt_pk_bf16_f32 v20, v22, v23
	v_cvt_pk_bf16_f32 v21, v24, v25
	s_nop 1
	v_permlane32_swap_b32_e32 v18, v20
	v_permlane32_swap_b32_e32 v19, v21
	s_nop 0
	global_store_dwordx4 v[34:35], v[18:21], off
	v_mul_f32_e32 v26, v26, v1
	v_mul_f32_e32 v27, v27, v1
	v_mul_f32_e32 v28, v28, v1
	v_mul_f32_e32 v29, v29, v1
	v_mul_f32_e32 v30, v30, v1
	v_mul_f32_e32 v31, v31, v1
	v_mul_f32_e32 v32, v32, v1
	v_mul_f32_e32 v33, v33, v1
	v_cvt_pk_bf16_f32 v26, v26, v27
	v_cvt_pk_bf16_f32 v27, v28, v29
	v_cvt_pk_bf16_f32 v28, v30, v31
	v_cvt_pk_bf16_f32 v29, v32, v33
	s_nop 1
	v_permlane32_swap_b32_e32 v26, v28
	v_permlane32_swap_b32_e32 v27, v29
	s_nop 0
	global_store_dwordx4 v[34:35], v[26:29], off offset:32
	v_mul_f32_e32 v2, v2, v1
	v_mul_f32_e32 v3, v3, v1
	v_mul_f32_e32 v4, v4, v1
	v_mul_f32_e32 v5, v5, v1
	v_mul_f32_e32 v6, v6, v1
	v_mul_f32_e32 v7, v7, v1
	v_mul_f32_e32 v8, v8, v1
	v_mul_f32_e32 v9, v9, v1
	v_cvt_pk_bf16_f32 v2, v2, v3
	v_cvt_pk_bf16_f32 v3, v4, v5
	v_cvt_pk_bf16_f32 v4, v6, v7
	v_cvt_pk_bf16_f32 v5, v8, v9
	s_nop 1
	v_permlane32_swap_b32_e32 v2, v4
	v_permlane32_swap_b32_e32 v3, v5
	s_nop 0
	global_store_dwordx4 v[34:35], v[2:5], off offset:64
	v_mul_f32_e32 v10, v10, v1
	v_mul_f32_e32 v11, v11, v1
	v_mul_f32_e32 v12, v12, v1
	v_mul_f32_e32 v13, v13, v1
	v_mul_f32_e32 v14, v14, v1
	v_mul_f32_e32 v15, v15, v1
	v_mul_f32_e32 v16, v16, v1
	v_mul_f32_e32 v17, v17, v1
	v_cvt_pk_bf16_f32 v10, v10, v11
	v_cvt_pk_bf16_f32 v11, v12, v13
	v_cvt_pk_bf16_f32 v12, v14, v15
	v_cvt_pk_bf16_f32 v13, v16, v17
	s_nop 1
	v_permlane32_swap_b32_e32 v10, v12
	v_permlane32_swap_b32_e32 v11, v13
	s_nop 0
	global_store_dwordx4 v[34:35], v[10:13], off offset:96
	s_cbranch_scc1 .LBB0_240
